# Layer 0 too: Q/K/V^T written as MFMA fragment images by the projection GEMM epilogues; attn0 LDS-DMA pieces and Q loads are 1 KiB contiguous
# speedup vs baseline: 1.0433x; 1.0274x over previous
.LBB0_431:
	v_writelane_b32 v255, s76, 19
	s_and_b32 s33, s7, -2
	v_writelane_b32 v255, s75, 20
	s_lshr_b32 s77, 0x80, s33
	s_lshl_b32 s75, s71, 10
	s_sub_i32 s76, 12, s33
	s_add_i32 s77, s77, -1
	s_add_i32 s75, s75, 0
	s_add_u32 s4, s0, 0x19000000
	s_addc_u32 s5, s1, 0
	v_writelane_b32 v255, s7, 21
	s_and_b64 s[2:3], exec, s[2:3]
	s_cselect_b32 s3, s83, s5
	v_writelane_b32 v255, s82, 22
	s_cselect_b32 s2, s82, s4
	s_add_u32 s4, s0, 0xb00000
	v_writelane_b32 v255, s83, 23
	v_writelane_b32 v255, s4, 24
	s_addc_u32 s4, s1, 0
	s_cmp_gt_i32 s71, 3
	v_lshlrev_b32_e32 v2, 1, v243
	v_lshrrev_b32_e32 v4, 5, v243
	s_cselect_b64 s[92:93], -1, 0
	s_lshl_b32 s6, s71, 4
	v_writelane_b32 v255, s4, 25
	v_and_b32_e32 v8, 8, v2
	v_lshlrev_b32_e32 v2, 3, v4
	v_lshlrev_b32_e32 v4, 4, v243
	v_mov_b32_e32 v5, v0
	s_ashr_i32 s7, s6, 31
	s_add_i32 s4, s6, 0x7fffffc0
	v_lshl_add_u64 v[6:7], s[2:3], 0, v[4:5]
	s_lshl_b32 s2, s71, 5
	v_writelane_b32 v255, s6, 26
	s_and_b32 s78, s2, 0x60
	s_lshl_b32 s78, s78, 5
	s_lshl_b32 s2, -1, s76
	v_writelane_b32 v255, s7, 27
	s_not_b32 s73, s2
	v_readlane_b32 s2, v255, 17
	v_lshrrev_b32_e32 v1, 1, v242
	s_and_b32 s4, s4, 0x7fffffe0
	v_mov_b32_e32 v3, v0
	v_readlane_b32 s3, v255, 18
	v_and_b32_e32 v150, 31, v242
	v_and_b32_e32 v1, 4, v1
	v_and_b32_e32 v9, 19, v242
	v_lshl_add_u64 v[116:117], v[6:7], 0, s[78:79]
	v_lshl_add_u64 v[118:119], s[2:3], 0, v[4:5]
	v_lshl_add_u64 v[120:121], s[18:19], 0, v[2:3]
	s_cmp_gt_i32 s10, 0
	v_or_b32_e32 v3, 2, v2
	v_or_b32_e32 v4, 3, v2
	v_or_b32_e32 v5, 4, v2
	v_or_b32_e32 v6, 5, v2
	v_or_b32_e32 v7, 6, v2
	v_or_b32_e32 v10, 7, v2
	v_or_b32_e32 v11, 16, v2
	s_waitcnt lgkmcnt(3)
	v_or_b32_e32 v12, 17, v2
	s_waitcnt lgkmcnt(2)
	v_or_b32_e32 v13, 18, v2
	s_waitcnt lgkmcnt(0)
	v_or_b32_e32 v14, 19, v2
	v_or_b32_e32 v15, 20, v2
	v_or_b32_e32 v16, 21, v2
	v_or_b32_e32 v17, 22, v2
	v_or_b32_e32 v18, 23, v2
	v_or_b32_e32 v19, 1, v2
	v_or_b32_e32 v151, s4, v150
	v_writelane_b32 v255, s10, 28
	s_cselect_b64 s[88:89], -1, 0
	v_lshl_add_u32 v152, v243, 4, 0
	v_cmp_gt_u32_e64 s[2:3], 32, v243
	v_cmp_gt_u32_e64 s[4:5], v2, v150
	v_cmp_lt_u32_e64 s[6:7], v2, v150
	v_cmp_gt_u32_e64 s[8:9], v3, v150
	v_cmp_gt_u32_e64 s[10:11], v4, v150
	v_cmp_gt_u32_e64 s[12:13], v5, v150
	v_cmp_gt_u32_e64 s[14:15], v6, v150
	v_cmp_gt_u32_e64 s[16:17], v7, v150
	v_cmp_gt_u32_e64 s[18:19], v10, v150
	v_cmp_gt_u32_e64 s[20:21], v11, v150
	v_cmp_gt_u32_e64 s[22:23], v12, v150
	v_cmp_gt_u32_e64 s[24:25], v13, v150
	v_cmp_gt_u32_e64 s[26:27], v14, v150
	v_cmp_gt_u32_e64 s[28:29], v15, v150
	v_cmp_gt_u32_e64 s[30:31], v16, v150
	v_cmp_gt_u32_e64 s[34:35], v17, v150
	v_cmp_gt_u32_e64 s[36:37], v18, v150
	v_cmp_lt_u32_e64 s[38:39], v19, v150
	v_cmp_lt_u32_e64 s[40:41], v3, v150
	v_cmp_lt_u32_e64 s[42:43], v4, v150
	v_cmp_lt_u32_e64 s[44:45], v5, v150
	v_cmp_lt_u32_e64 s[46:47], v6, v150
	v_cmp_lt_u32_e64 s[48:49], v7, v150
	v_cmp_lt_u32_e64 s[50:51], v10, v150
	v_cmp_lt_u32_e64 s[52:53], v11, v150
	v_cmp_lt_u32_e64 s[54:55], v12, v150
	v_cmp_lt_u32_e64 s[56:57], v13, v150
	v_cmp_lt_u32_e64 s[58:59], v14, v150
	v_cmp_lt_u32_e64 s[60:61], v15, v150
	v_cmp_lt_u32_e64 s[62:63], v16, v150
	v_cmp_lt_u32_e64 s[64:65], v17, v150
	v_cmp_lt_u32_e64 s[66:67], v18, v150
	v_or3_b32 v153, v1, v9, v8
	s_lshl_b32 s86, s70, 6
	v_lshlrev_b32_e32 v122, 1, v2
	s_branch .LBB0_433

.LBB0_433:
	s_ashr_i32 s74, s70, 5
	s_bfe_u32 s72, s70, 0x40001
	s_mov_b64 s[68:69], -1
	s_and_b64 vcc, exec, s[92:93]
	s_cbranch_vccz .LBB0_435
	s_lshl_b32 s68, s74, 4
	s_lshl_b32 s78, s72, 6
	s_add_i32 s68, s68, s72
	s_lshl_b32 s68, s68, 19
	s_mov_b32 s69, 0
	v_lshl_add_u64 v[140:141], v[116:117], 0, s[68:69]
	s_lshl_b32 s87, s74, 12
	s_mov_b64 s[68:69], 0
.LBB0_435:
	s_andn2_b64 vcc, exec, s[68:69]
	s_mov_b64 s[68:69], 0x800
	s_cbranch_vccnz .LBB0_437
	s_lshl_b32 s87, s74, 12
	v_lshlrev_b32_e32 v2, 4, v243
	v_mov_b32_e32 v3, v0
	v_readlane_b32 s68, v255, 17
	v_readlane_b32 s69, v255, 18
	v_mov_b32_e32 v123, v0
	s_lshl_b32 s78, s72, 6
	s_nop 1
	v_lshl_add_u64 v[2:3], s[68:69], 0, v[2:3]
	s_lshl_b32 s68, s74, 4
	s_add_i32 s68, s68, s72
	s_lshl_b32 s68, s68, 19
	s_lshl_b32 s69, s71, 10
	s_add_i32 s68, s68, s69
	s_or_b32 s68, s68, 0x4000000
	s_mov_b32 s69, 0
	v_lshl_add_u64 v[140:141], v[2:3], 0, s[68:69]
	s_mov_b64 s[68:69], 0x800
.LBB0_437:
	s_lshl_b32 s98, s74, 4
	s_add_i32 s98, s98, s72
	s_lshl_b32 s98, s98, 19
	s_mov_b32 s99, 0
	s_lshl_b32 s69, s86, 13
	s_and_b32 s69, s69, 0x80000
	s_or_b32 s84, s69, 0x20000
	s_lshl_b32 s69, s70, 6
	s_and_b32 s94, s69, 64
	s_lshl_b64 s[82:83], s[78:79], 1
	s_lshl_b32 s69, s72, 2
	v_readlane_b32 s72, v255, 24
	v_lshl_add_u64 v[142:143], v[118:119], 0, s[98:99]
	v_lshl_add_u64 v[144:145], v[120:121], 0, s[82:83]
	s_add_u32 s82, s72, s69
	v_readlane_b32 s69, v255, 25
	v_or_b32_e32 v123, s87, v150
	s_addc_u32 s83, s69, 0
	s_lshl_b32 s78, s68, 1
	s_mov_b32 s95, 0
	s_branch .LBB0_439

.LBB0_440:
	s_and_b32 vcc_lo, s85, 0x1e000
	s_add_i32 vcc_lo, s75, vcc_lo
	s_mov_b32 vcc_hi, m0
	s_mov_b32 m0, vcc_lo
	s_nop 0
	global_load_lds_dwordx4 v[2:3], off
	s_mov_b32 m0, vcc_hi
	s_add_i32 s69, s69, 1
	s_addk_i32 s85, 0x2000
	s_cmp_ge_i32 s69, s68
	v_lshl_add_u64 v[2:3], v[2:3], 0, s[78:79]
	s_cbranch_scc0 .LBB0_440
	s_add_i32 s72, s72, s71
	s_lshl_b32 s68, s72, 5
	s_lshl_b32 s98, s72, 12
	s_mov_b32 s99, 0
	v_lshl_add_u64 v[2:3], v[142:143], 0, s[98:99]
	global_load_dwordx4 v[92:95], v[2:3], off
	global_load_dwordx4 v[88:91], v[2:3], off offset:1024
	global_load_dwordx4 v[84:87], v[2:3], off offset:2048
	global_load_dwordx4 v[80:83], v[2:3], off offset:3072
	s_ashr_i32 s69, s68, s76
	s_and_b32 s68, s68, s73
	v_or_b32_e32 v1, s68, v150
	v_lshlrev_b32_e32 v1, s33, v1
	s_add_i32 s69, s69, s87
	v_add_u32_e32 v2, s69, v1
	v_ashrrev_i32_e32 v3, 31, v2
	v_lshlrev_b64 v[4:5], 11, v[2:3]
	v_lshlrev_b64 v[2:3], 6, v[2:3]
	v_lshl_add_u64 v[148:149], v[144:145], 0, v[4:5]
	s_and_b64 vcc, exec, s[88:89]
	v_lshl_add_u64 v[146:147], s[82:83], 0, v[2:3]
	s_cbranch_vccz .LBB0_443
	global_load_dword v154, v[146:147], off
	global_load_dwordx2 v[138:139], v[148:149], off
	global_load_dwordx2 v[136:137], v[148:149], off offset:16
	global_load_dwordx2 v[134:135], v[148:149], off offset:32
	global_load_dwordx2 v[132:133], v[148:149], off offset:48
	global_load_dwordx2 v[130:131], v[148:149], off offset:64
	global_load_dwordx2 v[128:129], v[148:149], off offset:80
	global_load_dwordx2 v[126:127], v[148:149], off offset:96
	global_load_dwordx2 v[124:125], v[148:149], off offset:112
	s_branch .LBB0_444

.LBB0_515:
	s_lshr_b32 s98, s33, 2
	s_lshl_b32 s98, s98, 26
	s_lshr_b32 s99, s52, 4
	s_lshl_b32 s99, s99, 4
	s_and_b32 s100, s33, 3
	s_lshl_b32 s100, s100, 2
	s_add_i32 s99, s99, s100
	s_and_b32 s100, s71, 3
	s_lshr_b32 s100, s100, 1
	s_add_i32 s99, s99, s100
	s_lshl_b32 s99, s99, 19
	s_add_u32 s98, s98, s99
	s_and_b32 s99, s52, 15
	s_lshl_b32 s99, s99, 15
	s_add_u32 s98, s98, s99
	s_lshr_b32 s99, s71, 2
	s_lshl_b32 s99, s99, 13
	s_add_u32 s98, s98, s99
	s_and_b32 s99, s71, 1
	s_lshl_b32 s99, s99, 11
	s_add_u32 s98, s98, s99
	s_add_u32 s98, s96, s98
	s_addc_u32 s99, s97, 0
	s_mov_b32 s100, 0x100000
	s_mov_b32 s101, 0
	s_lshl_b32 s26, s52, 8
	v_add_u32_e32 v176, s26, v204
	v_ashrrev_i32_e32 v177, 31, v176
	v_lshl_add_u64 v[38:39], v[176:177], 2, s[8:9]
	global_load_dword v178, v[38:39], off
	global_load_dword v215, v[38:39], off offset:64
	global_load_dword v214, v[38:39], off offset:128
	global_load_dword v213, v[38:39], off offset:192
	global_load_dword v212, v[38:39], off offset:512
	global_load_dword v211, v[38:39], off offset:576
	global_load_dword v210, v[38:39], off offset:640
	global_load_dword v208, v[38:39], off offset:704
	v_cndmask_b32_e64 v38, 0, 1, s[18:19]
	v_cmp_ne_u32_e64 s[6:7], 1, v38
	s_andn2_b64 vcc, exec, s[18:19]
	s_waitcnt vmcnt(0)
	s_cbranch_vccnz .LBB0_517
	s_add_i32 s24, s26, s43
	s_and_b32 s24, s24, 0xfc0
	v_or_b32_e32 v38, s24, v188
	v_lshlrev_b32_e32 v39, s30, v38
	v_and_b32_e32 v39, 0xfff, v39
	v_lshrrev_b32_e32 v40, s37, v38
	v_add_lshl_u32 v39, v39, v40, 6
	v_or_b32_e32 v38, 16, v38
	global_load_dwordx4 v[66:69], v39, s[0:1] offset:48
	global_load_dwordx4 v[70:73], v39, s[0:1] offset:32
	global_load_dwordx4 v[78:81], v39, s[0:1] offset:16
	global_load_dwordx4 v[82:85], v39, s[0:1]
	v_lshlrev_b32_e32 v39, s30, v38
	v_and_b32_e32 v39, 0xfff, v39
	v_lshrrev_b32_e32 v38, s37, v38
	v_add_lshl_u32 v54, v39, v38, 6
	global_load_dwordx4 v[38:41], v54, s[0:1] offset:48
	global_load_dwordx4 v[42:45], v54, s[0:1] offset:32
	global_load_dwordx4 v[50:53], v54, s[0:1] offset:16
	s_nop 0
	global_load_dwordx4 v[54:57], v54, s[0:1]
	s_waitcnt vmcnt(0)

.LBB0_525:
	v_and_b32_e32 v154, 15, v204
	v_and_b32_e32 v194, 3, v154
	v_and_b32_e32 v195, 4, v154
	v_lshl_or_b32 v194, v195, 1, v194
	v_and_b32_e32 v195, 8, v154
	v_lshrrev_b32_e32 v195, 1, v195
	v_or_b32_e32 v194, v194, v195
	s_cmp_lt_i32 s33, 4
	s_cselect_b64 vcc, -1, 0
	v_cndmask_b32_e32 v154, v194, v154, vcc
	v_lshlrev_b32_e32 v154, 4, v154
	v_and_b32_e32 v194, 31, v206
	v_lshl_add_u32 v154, v194, 6, v154
	v_lshrrev_b32_e32 v154, 1, v154
	v_mov_b64_e32 v[194:195], 0
	s_waitcnt lgkmcnt(3)
	s_waitcnt lgkmcnt(2)
	v_ashrrev_i32_e32 v155, 31, v154
	v_cvt_pk_bf16_f32 v158, v158, v159
	v_cvt_pk_bf16_f32 v159, v160, v161
	v_cvt_pk_bf16_f32 v160, v156, v157
	v_lshl_add_u64 v[156:157], s[98:99], 0, v[194:195]
	v_cvt_pk_bf16_f32 v161, v182, v183
	v_lshl_add_u64 v[156:157], v[154:155], 1, v[156:157]
	v_pk_mul_f32 v[152:153], v[152:153], v[180:181]
	s_and_b64 vcc, exec, s[6:7]
	v_pk_mul_f32 v[150:151], v[150:151], v[178:179]
	global_store_dwordx4 v[156:157], v[158:161], off
	s_cbranch_vccnz .LBB0_529
	s_nop 0
	v_and_b32_e32 v159, 64, v238
	v_xor_b32_e32 v158, 16, v238
	v_add_u32_e32 v159, 64, v159
	v_cmp_lt_i32_e32 vcc, v158, v159
	s_nop 1
	v_cndmask_b32_e32 v158, v238, v158, vcc
	v_lshlrev_b32_e32 v160, 2, v158
	ds_bpermute_b32 v158, v160, v150
	ds_bpermute_b32 v159, v160, v151
	ds_bpermute_b32 v161, v160, v152
	ds_bpermute_b32 v160, v160, v153
	s_and_saveexec_b64 s[24:25], s[2:3]
	s_cbranch_execz .LBB0_528
	s_waitcnt lgkmcnt(2)
	v_pk_mul_f32 v[158:159], v[170:171], v[158:159]
	v_mov_b32_e32 v182, v83
	v_mov_b32_e32 v183, v85
	v_mov_b32_e32 v180, v82
	v_mov_b32_e32 v181, v84
	v_pk_mul_f32 v[158:159], v[182:183], v[158:159]
	v_mul_f32_e32 v152, v152, v78
	v_pk_fma_f32 v[150:151], v[150:151], v[180:181], v[158:159]
	s_waitcnt lgkmcnt(1)
	v_mul_f32_e32 v158, v170, v161
	s_waitcnt lgkmcnt(0)
	v_mul_f32_e32 v161, v170, v160
	v_mov_b32_e32 v180, v153
	v_mov_b32_e32 v181, v81
	v_mov_b32_e32 v160, v80
	v_pk_mul_f32 v[160:161], v[180:181], v[160:161]
	v_mul_f32_e32 v158, v79, v158
	v_mov_b32_e32 v153, v160
	v_mov_b32_e32 v159, v161
	v_pk_add_f32 v[152:153], v[152:153], v[158:159]

.LBB0_533:
	s_waitcnt lgkmcnt(3)
	v_mul_f32_e32 v146, v209, v215
	v_cvt_pk_bf16_f32 v150, v150, v151
	v_cvt_pk_bf16_f32 v151, v152, v153
	v_cvt_pk_bf16_f32 v152, v148, v149
	v_cvt_pk_bf16_f32 v153, v158, v159
	s_waitcnt lgkmcnt(2)
	v_pk_mul_f32 v[144:145], v[144:145], v[146:147] op_sel_hi:[1,0]
	s_and_b64 vcc, exec, s[6:7]
	v_pk_mul_f32 v[142:143], v[142:143], v[146:147] op_sel_hi:[1,0]
	v_lshl_add_u64 v[156:157], v[156:157], 0, s[100:101]
	global_store_dwordx4 v[156:157], v[150:153], off
	s_cbranch_vccnz .LBB0_537
	v_and_b32_e32 v148, 64, v238
	v_xor_b32_e32 v147, 16, v238
	v_add_u32_e32 v148, 64, v148
	v_cmp_lt_i32_e32 vcc, v147, v148
	s_nop 1
	v_cndmask_b32_e32 v147, v238, v147, vcc
	v_lshlrev_b32_e32 v147, 2, v147
	ds_bpermute_b32 v148, v147, v142
	ds_bpermute_b32 v149, v147, v143
	ds_bpermute_b32 v150, v147, v144
	ds_bpermute_b32 v147, v147, v145
	s_and_saveexec_b64 s[24:25], s[2:3]
	s_cbranch_execz .LBB0_536
	s_waitcnt lgkmcnt(2)
	v_pk_mul_f32 v[148:149], v[170:171], v[148:149]
	v_mov_b32_e32 v156, v55
	v_mov_b32_e32 v157, v57
	v_mov_b32_e32 v152, v54
	v_mov_b32_e32 v153, v56
	v_pk_mul_f32 v[148:149], v[156:157], v[148:149]
	s_waitcnt lgkmcnt(0)
	v_mul_f32_e32 v151, v170, v147
	v_pk_fma_f32 v[142:143], v[142:143], v[152:153], v[148:149]
	v_mul_f32_e32 v148, v170, v150
	v_mov_b32_e32 v152, v145
	v_mov_b32_e32 v153, v53
	v_mov_b32_e32 v150, v52
	v_pk_mul_f32 v[150:151], v[152:153], v[150:151]
	v_mul_f32_e32 v144, v144, v50
	v_mul_f32_e32 v148, v51, v148
	v_mov_b32_e32 v145, v150
	v_mov_b32_e32 v149, v151
	v_pk_add_f32 v[144:145], v[144:145], v[148:149]

.LBB0_541:
	s_waitcnt lgkmcnt(3)
	v_or_b32_e32 v150, 16, v204
	v_add_u32_e32 v150, s26, v150
	s_waitcnt lgkmcnt(2)
	v_ashrrev_i32_e32 v151, 31, v150
	v_mov_b64_e32 v[150:151], 0x100
	v_cvt_pk_bf16_f32 v142, v142, v143
	v_cvt_pk_bf16_f32 v143, v144, v145
	v_cvt_pk_bf16_f32 v144, v138, v139
	v_lshl_add_u64 v[138:139], s[98:99], 0, v[150:151]
	v_cvt_pk_bf16_f32 v145, v140, v141
	v_lshl_add_u64 v[138:139], v[154:155], 1, v[138:139]
	v_pk_mul_f32 v[136:137], v[136:137], v[148:149]
	s_and_b64 vcc, exec, s[6:7]
	v_pk_mul_f32 v[134:135], v[134:135], v[146:147]
	global_store_dwordx4 v[138:139], v[142:145], off
	s_cbranch_vccnz .LBB0_545
	v_and_b32_e32 v141, 64, v238
	v_xor_b32_e32 v140, 16, v238
	v_add_u32_e32 v141, 64, v141
	v_cmp_lt_i32_e32 vcc, v140, v141
	s_nop 1
	v_cndmask_b32_e32 v140, v238, v140, vcc
	v_lshlrev_b32_e32 v142, 2, v140
	ds_bpermute_b32 v140, v142, v134
	ds_bpermute_b32 v141, v142, v135
	ds_bpermute_b32 v143, v142, v136
	ds_bpermute_b32 v142, v142, v137
	s_and_saveexec_b64 s[24:25], s[2:3]
	s_cbranch_execz .LBB0_544
	s_waitcnt lgkmcnt(2)
	v_pk_mul_f32 v[140:141], v[170:171], v[140:141]
	v_mov_b32_e32 v148, v55
	v_mov_b32_e32 v149, v57
	v_mov_b32_e32 v144, v54
	v_mov_b32_e32 v145, v56
	v_pk_mul_f32 v[140:141], v[148:149], v[140:141]
	v_mul_f32_e32 v136, v136, v50
	v_pk_fma_f32 v[134:135], v[134:135], v[144:145], v[140:141]
	s_waitcnt lgkmcnt(1)
	v_mul_f32_e32 v140, v170, v143
	s_waitcnt lgkmcnt(0)
	v_mul_f32_e32 v143, v170, v142
	v_mov_b32_e32 v144, v137
	v_mov_b32_e32 v145, v53
	v_mov_b32_e32 v142, v52
	v_pk_mul_f32 v[142:143], v[144:145], v[142:143]
	v_mul_f32_e32 v140, v51, v140
	v_mov_b32_e32 v137, v142
	v_mov_b32_e32 v141, v143
	v_pk_add_f32 v[136:137], v[136:137], v[140:141]

.LBB0_549:
	v_cvt_pk_bf16_f32 v134, v134, v135
	v_cvt_pk_bf16_f32 v135, v136, v137
	v_cvt_pk_bf16_f32 v136, v130, v131
	v_cvt_pk_bf16_f32 v137, v132, v133
	s_and_b64 vcc, exec, s[6:7]
	v_lshl_add_u64 v[138:139], v[138:139], 0, s[100:101]
	global_store_dwordx4 v[138:139], v[134:137], off
	s_cbranch_vccnz .LBB0_551
	s_add_i32 s24, s26, s43
	s_and_b32 s24, s24, 0xfc0
	v_or_b32_e32 v38, s24, v188
	v_or_b32_e32 v39, 32, v38
	v_lshlrev_b32_e32 v40, s30, v39
	v_and_b32_e32 v40, 0xfff, v40
	v_lshrrev_b32_e32 v39, s37, v39
	v_add_lshl_u32 v39, v40, v39, 6
	v_or_b32_e32 v38, 48, v38
	global_load_dwordx4 v[66:69], v39, s[0:1] offset:48
	global_load_dwordx4 v[70:73], v39, s[0:1] offset:32
	global_load_dwordx4 v[78:81], v39, s[0:1] offset:16
	global_load_dwordx4 v[82:85], v39, s[0:1]
	v_lshlrev_b32_e32 v39, s30, v38
	v_and_b32_e32 v39, 0xfff, v39
	v_lshrrev_b32_e32 v38, s37, v38
	v_add_lshl_u32 v54, v39, v38, 6
	global_load_dwordx4 v[38:41], v54, s[0:1] offset:48
	global_load_dwordx4 v[42:45], v54, s[0:1] offset:32
	global_load_dwordx4 v[50:53], v54, s[0:1] offset:16
	s_nop 0
	global_load_dwordx4 v[54:57], v54, s[0:1]
	s_waitcnt vmcnt(0)

.LBB0_559:
	s_waitcnt lgkmcnt(3)
	v_or_b32_e32 v134, 32, v204
	v_add_u32_e32 v134, s26, v134
	s_waitcnt lgkmcnt(2)
	v_ashrrev_i32_e32 v135, 31, v134
	v_mov_b64_e32 v[134:135], 0x1000
	v_cvt_pk_bf16_f32 v126, v126, v127
	v_cvt_pk_bf16_f32 v127, v128, v129
	v_cvt_pk_bf16_f32 v128, v122, v123
	v_lshl_add_u64 v[122:123], s[98:99], 0, v[134:135]
	v_cvt_pk_bf16_f32 v129, v124, v125
	v_lshl_add_u64 v[122:123], v[154:155], 1, v[122:123]
	v_pk_mul_f32 v[120:121], v[120:121], v[132:133]
	s_and_b64 vcc, exec, s[6:7]
	v_pk_mul_f32 v[118:119], v[118:119], v[130:131]
	global_store_dwordx4 v[122:123], v[126:129], off
	s_cbranch_vccnz .LBB0_563
	v_and_b32_e32 v125, 64, v238
	v_xor_b32_e32 v124, 16, v238
	v_add_u32_e32 v125, 64, v125
	v_cmp_lt_i32_e32 vcc, v124, v125
	s_nop 1
	v_cndmask_b32_e32 v124, v238, v124, vcc
	v_lshlrev_b32_e32 v126, 2, v124
	ds_bpermute_b32 v124, v126, v118
	ds_bpermute_b32 v125, v126, v119
	ds_bpermute_b32 v127, v126, v120
	ds_bpermute_b32 v126, v126, v121
	s_and_saveexec_b64 s[24:25], s[2:3]
	s_cbranch_execz .LBB0_562
	s_waitcnt lgkmcnt(2)
	v_pk_mul_f32 v[124:125], v[170:171], v[124:125]
	v_mov_b32_e32 v132, v83
	v_mov_b32_e32 v133, v85
	v_mov_b32_e32 v128, v82
	v_mov_b32_e32 v129, v84
	v_pk_mul_f32 v[124:125], v[132:133], v[124:125]
	v_mul_f32_e32 v120, v120, v78
	v_pk_fma_f32 v[118:119], v[118:119], v[128:129], v[124:125]
	s_waitcnt lgkmcnt(1)
	v_mul_f32_e32 v124, v170, v127
	s_waitcnt lgkmcnt(0)
	v_mul_f32_e32 v127, v170, v126
	v_mov_b32_e32 v128, v121
	v_mov_b32_e32 v129, v81
	v_mov_b32_e32 v126, v80
	v_pk_mul_f32 v[126:127], v[128:129], v[126:127]
	v_mul_f32_e32 v124, v79, v124
	v_mov_b32_e32 v121, v126
	v_mov_b32_e32 v125, v127
	v_pk_add_f32 v[120:121], v[120:121], v[124:125]

.LBB0_567:
	s_waitcnt lgkmcnt(3)
	v_mul_f32_e32 v114, v209, v213
	v_cvt_pk_bf16_f32 v118, v118, v119
	v_cvt_pk_bf16_f32 v119, v120, v121
	v_cvt_pk_bf16_f32 v120, v116, v117
	v_cvt_pk_bf16_f32 v121, v124, v125
	s_waitcnt lgkmcnt(2)
	v_pk_mul_f32 v[112:113], v[112:113], v[114:115] op_sel_hi:[1,0]
	s_and_b64 vcc, exec, s[6:7]
	v_pk_mul_f32 v[110:111], v[110:111], v[114:115] op_sel_hi:[1,0]
	v_lshl_add_u64 v[122:123], v[122:123], 0, s[100:101]
	global_store_dwordx4 v[122:123], v[118:121], off
	s_cbranch_vccnz .LBB0_571
	v_and_b32_e32 v116, 64, v238
	v_xor_b32_e32 v115, 16, v238
	v_add_u32_e32 v116, 64, v116
	v_cmp_lt_i32_e32 vcc, v115, v116
	s_nop 1
	v_cndmask_b32_e32 v115, v238, v115, vcc
	v_lshlrev_b32_e32 v115, 2, v115
	ds_bpermute_b32 v116, v115, v110
	ds_bpermute_b32 v117, v115, v111
	ds_bpermute_b32 v118, v115, v112
	ds_bpermute_b32 v115, v115, v113
	s_and_saveexec_b64 s[24:25], s[2:3]
	s_cbranch_execz .LBB0_570
	s_waitcnt lgkmcnt(2)
	v_pk_mul_f32 v[116:117], v[170:171], v[116:117]
	v_mov_b32_e32 v122, v55
	v_mov_b32_e32 v123, v57
	v_mov_b32_e32 v120, v54
	v_mov_b32_e32 v121, v56
	v_pk_mul_f32 v[116:117], v[122:123], v[116:117]
	s_waitcnt lgkmcnt(0)
	v_mul_f32_e32 v119, v170, v115
	v_pk_fma_f32 v[110:111], v[110:111], v[120:121], v[116:117]
	v_mul_f32_e32 v116, v170, v118
	v_mov_b32_e32 v120, v113
	v_mov_b32_e32 v121, v53
	v_mov_b32_e32 v118, v52
	v_pk_mul_f32 v[118:119], v[120:121], v[118:119]
	v_mul_f32_e32 v112, v112, v50
	v_mul_f32_e32 v116, v51, v116
	v_mov_b32_e32 v113, v118
	v_mov_b32_e32 v117, v119
	v_pk_add_f32 v[112:113], v[112:113], v[116:117]

.LBB0_575:
	s_waitcnt lgkmcnt(3)
	v_or_b32_e32 v118, 48, v204
	v_add_u32_e32 v118, s26, v118
	s_waitcnt lgkmcnt(2)
	v_ashrrev_i32_e32 v119, 31, v118
	v_mov_b64_e32 v[118:119], 0x1100
	v_cvt_pk_bf16_f32 v110, v110, v111
	v_cvt_pk_bf16_f32 v111, v112, v113
	v_cvt_pk_bf16_f32 v112, v106, v107
	v_lshl_add_u64 v[106:107], s[98:99], 0, v[118:119]
	v_cvt_pk_bf16_f32 v113, v108, v109
	v_lshl_add_u64 v[106:107], v[154:155], 1, v[106:107]
	v_pk_mul_f32 v[104:105], v[104:105], v[116:117]
	s_and_b64 vcc, exec, s[6:7]
	v_pk_mul_f32 v[102:103], v[102:103], v[114:115]
	global_store_dwordx4 v[106:107], v[110:113], off
	s_cbranch_vccnz .LBB0_579
	v_and_b32_e32 v109, 64, v238
	v_xor_b32_e32 v108, 16, v238
	v_add_u32_e32 v109, 64, v109
	v_cmp_lt_i32_e32 vcc, v108, v109
	s_nop 1
	v_cndmask_b32_e32 v108, v238, v108, vcc
	v_lshlrev_b32_e32 v110, 2, v108
	ds_bpermute_b32 v108, v110, v102
	ds_bpermute_b32 v109, v110, v103
	ds_bpermute_b32 v111, v110, v104
	ds_bpermute_b32 v110, v110, v105
	s_and_saveexec_b64 s[24:25], s[2:3]
	s_cbranch_execz .LBB0_578
	s_waitcnt lgkmcnt(2)
	v_pk_mul_f32 v[108:109], v[170:171], v[108:109]
	v_mov_b32_e32 v116, v55
	v_mov_b32_e32 v117, v57
	v_mov_b32_e32 v112, v54
	v_mov_b32_e32 v113, v56
	v_pk_mul_f32 v[108:109], v[116:117], v[108:109]
	v_mul_f32_e32 v104, v104, v50
	v_pk_fma_f32 v[102:103], v[102:103], v[112:113], v[108:109]
	s_waitcnt lgkmcnt(1)
	v_mul_f32_e32 v108, v170, v111
	s_waitcnt lgkmcnt(0)
	v_mul_f32_e32 v111, v170, v110
	v_mov_b32_e32 v112, v105
	v_mov_b32_e32 v113, v53
	v_mov_b32_e32 v110, v52
	v_pk_mul_f32 v[110:111], v[112:113], v[110:111]
	v_mul_f32_e32 v108, v51, v108
	v_mov_b32_e32 v105, v110
	v_mov_b32_e32 v109, v111
	v_pk_add_f32 v[104:105], v[104:105], v[108:109]

.LBB0_583:
	v_cvt_pk_bf16_f32 v102, v102, v103
	v_cvt_pk_bf16_f32 v103, v104, v105
	v_cvt_pk_bf16_f32 v104, v98, v99
	v_cvt_pk_bf16_f32 v105, v100, v101
	s_and_b64 vcc, exec, s[6:7]
	v_lshl_add_u64 v[106:107], v[106:107], 0, s[100:101]
	global_store_dwordx4 v[106:107], v[102:105], off
	s_cbranch_vccnz .LBB0_585
	s_add_i32 s24, s26, s47
	s_and_b32 s24, s24, 0xfc0
	v_or_b32_e32 v38, s24, v188
	v_lshlrev_b32_e32 v39, s30, v38
	v_and_b32_e32 v39, 0xfff, v39
	v_lshrrev_b32_e32 v40, s37, v38
	v_add_lshl_u32 v39, v39, v40, 6
	v_or_b32_e32 v38, 16, v38
	global_load_dwordx4 v[66:69], v39, s[0:1] offset:48
	global_load_dwordx4 v[70:73], v39, s[0:1] offset:32
	global_load_dwordx4 v[78:81], v39, s[0:1] offset:16
	global_load_dwordx4 v[82:85], v39, s[0:1]
	v_lshlrev_b32_e32 v39, s30, v38
	v_and_b32_e32 v39, 0xfff, v39
	v_lshrrev_b32_e32 v38, s37, v38
	v_add_lshl_u32 v54, v39, v38, 6
	global_load_dwordx4 v[38:41], v54, s[0:1] offset:48
	global_load_dwordx4 v[42:45], v54, s[0:1] offset:32
	global_load_dwordx4 v[50:53], v54, s[0:1] offset:16
	s_nop 0
	global_load_dwordx4 v[54:57], v54, s[0:1]
	s_waitcnt vmcnt(0)

.LBB0_593:
	s_waitcnt lgkmcnt(3)
	v_add_u32_e32 v102, 0x80, v176
	s_waitcnt lgkmcnt(2)
	v_ashrrev_i32_e32 v103, 31, v102
	v_mov_b64_e32 v[102:103], 0x4000
	v_cvt_pk_bf16_f32 v94, v94, v95
	v_cvt_pk_bf16_f32 v95, v96, v97
	v_cvt_pk_bf16_f32 v96, v90, v91
	v_lshl_add_u64 v[90:91], s[98:99], 0, v[102:103]
	v_cvt_pk_bf16_f32 v97, v92, v93
	v_lshl_add_u64 v[90:91], v[154:155], 1, v[90:91]
	v_pk_mul_f32 v[88:89], v[88:89], v[100:101]
	s_and_b64 vcc, exec, s[6:7]
	v_pk_mul_f32 v[86:87], v[86:87], v[98:99]
	global_store_dwordx4 v[90:91], v[94:97], off
	s_cbranch_vccnz .LBB0_597
	v_and_b32_e32 v93, 64, v238
	v_xor_b32_e32 v92, 16, v238
	v_add_u32_e32 v93, 64, v93
	v_cmp_lt_i32_e32 vcc, v92, v93
	s_nop 1
	v_cndmask_b32_e32 v92, v238, v92, vcc
	v_lshlrev_b32_e32 v94, 2, v92
	ds_bpermute_b32 v92, v94, v86
	ds_bpermute_b32 v93, v94, v87
	ds_bpermute_b32 v95, v94, v88
	ds_bpermute_b32 v94, v94, v89
	s_and_saveexec_b64 s[24:25], s[2:3]
	s_cbranch_execz .LBB0_596
	s_waitcnt lgkmcnt(2)
	v_pk_mul_f32 v[92:93], v[170:171], v[92:93]
	v_mov_b32_e32 v100, v83
	v_mov_b32_e32 v101, v85
	v_mov_b32_e32 v96, v82
	v_mov_b32_e32 v97, v84
	v_pk_mul_f32 v[92:93], v[100:101], v[92:93]
	v_mul_f32_e32 v88, v88, v78
	v_pk_fma_f32 v[86:87], v[86:87], v[96:97], v[92:93]
	s_waitcnt lgkmcnt(1)
	v_mul_f32_e32 v92, v170, v95
	s_waitcnt lgkmcnt(0)
	v_mul_f32_e32 v95, v170, v94
	v_mov_b32_e32 v96, v89
	v_mov_b32_e32 v97, v81
	v_mov_b32_e32 v94, v80
	v_pk_mul_f32 v[94:95], v[96:97], v[94:95]
	v_mul_f32_e32 v92, v79, v92
	v_mov_b32_e32 v89, v94
	v_mov_b32_e32 v93, v95
	v_pk_add_f32 v[88:89], v[88:89], v[92:93]

.LBB0_601:
	s_waitcnt lgkmcnt(3)
	v_mul_f32_e32 v74, v209, v211
	v_cvt_pk_bf16_f32 v86, v86, v87
	v_cvt_pk_bf16_f32 v87, v88, v89
	v_cvt_pk_bf16_f32 v88, v76, v77
	v_cvt_pk_bf16_f32 v89, v92, v93
	s_waitcnt lgkmcnt(2)
	v_pk_mul_f32 v[64:65], v[64:65], v[74:75] op_sel_hi:[1,0]
	s_and_b64 vcc, exec, s[6:7]
	v_pk_mul_f32 v[62:63], v[62:63], v[74:75] op_sel_hi:[1,0]
	v_lshl_add_u64 v[90:91], v[90:91], 0, s[100:101]
	global_store_dwordx4 v[90:91], v[86:89], off
	s_cbranch_vccnz .LBB0_605
	v_and_b32_e32 v76, 64, v238
	v_xor_b32_e32 v75, 16, v238
	v_add_u32_e32 v76, 64, v76
	v_cmp_lt_i32_e32 vcc, v75, v76
	s_nop 1
	v_cndmask_b32_e32 v75, v238, v75, vcc
	v_lshlrev_b32_e32 v75, 2, v75
	ds_bpermute_b32 v76, v75, v62
	ds_bpermute_b32 v77, v75, v63
	ds_bpermute_b32 v86, v75, v64
	ds_bpermute_b32 v75, v75, v65
	s_and_saveexec_b64 s[24:25], s[2:3]
	s_cbranch_execz .LBB0_604
	s_waitcnt lgkmcnt(2)
	v_pk_mul_f32 v[76:77], v[170:171], v[76:77]
	v_mov_b32_e32 v90, v55
	v_mov_b32_e32 v91, v57
	v_mov_b32_e32 v88, v54
	v_mov_b32_e32 v89, v56
	v_pk_mul_f32 v[76:77], v[90:91], v[76:77]
	s_waitcnt lgkmcnt(0)
	v_mul_f32_e32 v87, v170, v75
	v_pk_fma_f32 v[62:63], v[62:63], v[88:89], v[76:77]
	v_mul_f32_e32 v76, v170, v86
	v_mov_b32_e32 v88, v65
	v_mov_b32_e32 v89, v53
	v_mov_b32_e32 v86, v52
	v_pk_mul_f32 v[86:87], v[88:89], v[86:87]
	v_mul_f32_e32 v64, v64, v50
	v_mul_f32_e32 v76, v51, v76
	v_mov_b32_e32 v65, v86
	v_mov_b32_e32 v77, v87
	v_pk_add_f32 v[64:65], v[64:65], v[76:77]

.LBB0_609:
	s_waitcnt lgkmcnt(3)
	v_add_u32_e32 v86, 0x90, v176
	s_waitcnt lgkmcnt(2)
	v_ashrrev_i32_e32 v87, 31, v86
	v_mov_b64_e32 v[86:87], 0x4100
	v_cvt_pk_bf16_f32 v62, v62, v63
	v_cvt_pk_bf16_f32 v63, v64, v65
	v_cvt_pk_bf16_f32 v64, v58, v59
	v_lshl_add_u64 v[58:59], s[98:99], 0, v[86:87]
	v_cvt_pk_bf16_f32 v65, v60, v61
	v_lshl_add_u64 v[58:59], v[154:155], 1, v[58:59]
	v_pk_mul_f32 v[48:49], v[48:49], v[76:77]
	s_and_b64 vcc, exec, s[6:7]
	v_pk_mul_f32 v[46:47], v[46:47], v[74:75]
	global_store_dwordx4 v[58:59], v[62:65], off
	s_cbranch_vccnz .LBB0_613
	v_and_b32_e32 v61, 64, v238
	v_xor_b32_e32 v60, 16, v238
	v_add_u32_e32 v61, 64, v61
	v_cmp_lt_i32_e32 vcc, v60, v61
	s_nop 1
	v_cndmask_b32_e32 v60, v238, v60, vcc
	v_lshlrev_b32_e32 v62, 2, v60
	ds_bpermute_b32 v60, v62, v46
	ds_bpermute_b32 v61, v62, v47
	ds_bpermute_b32 v63, v62, v48
	ds_bpermute_b32 v62, v62, v49
	s_and_saveexec_b64 s[24:25], s[2:3]
	s_cbranch_execz .LBB0_612
	s_waitcnt lgkmcnt(2)
	v_pk_mul_f32 v[60:61], v[170:171], v[60:61]
	v_mov_b32_e32 v76, v55
	v_mov_b32_e32 v77, v57
	v_mov_b32_e32 v64, v54
	v_mov_b32_e32 v65, v56
	v_pk_mul_f32 v[60:61], v[76:77], v[60:61]
	v_mul_f32_e32 v48, v48, v50
	v_pk_fma_f32 v[46:47], v[46:47], v[64:65], v[60:61]
	s_waitcnt lgkmcnt(1)
	v_mul_f32_e32 v60, v170, v63
	s_waitcnt lgkmcnt(0)
	v_mul_f32_e32 v63, v170, v62
	v_mov_b32_e32 v64, v49
	v_mov_b32_e32 v65, v53
	v_mov_b32_e32 v62, v52
	v_pk_mul_f32 v[62:63], v[64:65], v[62:63]
	v_mul_f32_e32 v60, v51, v60
	v_mov_b32_e32 v49, v62
	v_mov_b32_e32 v61, v63
	v_pk_add_f32 v[48:49], v[48:49], v[60:61]

.LBB0_617:
	v_cvt_pk_bf16_f32 v46, v46, v47
	v_cvt_pk_bf16_f32 v47, v48, v49
	v_cvt_pk_bf16_f32 v48, v34, v35
	v_cvt_pk_bf16_f32 v49, v36, v37
	s_and_b64 vcc, exec, s[6:7]
	v_lshl_add_u64 v[58:59], v[58:59], 0, s[100:101]
	global_store_dwordx4 v[58:59], v[46:49], off
	s_cbranch_vccnz .LBB0_619
	s_add_i32 s26, s26, s47
	s_and_b32 s24, s26, 0xfc0
	v_or_b32_e32 v34, s24, v188
	v_or_b32_e32 v35, 32, v34
	v_lshlrev_b32_e32 v36, s30, v35
	v_and_b32_e32 v36, 0xfff, v36
	v_lshrrev_b32_e32 v35, s37, v35
	v_add_lshl_u32 v35, v36, v35, 6
	v_or_b32_e32 v34, 48, v34
	global_load_dwordx4 v[66:69], v35, s[0:1] offset:48
	global_load_dwordx4 v[70:73], v35, s[0:1] offset:32
	global_load_dwordx4 v[78:81], v35, s[0:1] offset:16
	global_load_dwordx4 v[82:85], v35, s[0:1]
	v_lshlrev_b32_e32 v35, s30, v34
	v_and_b32_e32 v35, 0xfff, v35
	v_lshrrev_b32_e32 v34, s37, v34
	v_add_lshl_u32 v34, v35, v34, 6
	global_load_dwordx4 v[38:41], v34, s[0:1] offset:48
	global_load_dwordx4 v[42:45], v34, s[0:1] offset:32
	global_load_dwordx4 v[50:53], v34, s[0:1] offset:16
	global_load_dwordx4 v[54:57], v34, s[0:1]
	s_waitcnt vmcnt(0)

.LBB0_627:
	s_waitcnt lgkmcnt(3)
	v_add_u32_e32 v46, 0xa0, v176
	s_waitcnt lgkmcnt(2)
	v_ashrrev_i32_e32 v47, 31, v46
	v_mov_b64_e32 v[46:47], 0x5000
	v_cvt_pk_bf16_f32 v30, v30, v31
	v_cvt_pk_bf16_f32 v31, v32, v33
	v_cvt_pk_bf16_f32 v32, v26, v27
	v_lshl_add_u64 v[26:27], s[98:99], 0, v[46:47]
	v_cvt_pk_bf16_f32 v33, v28, v29
	v_lshl_add_u64 v[26:27], v[154:155], 1, v[26:27]
	v_pk_mul_f32 v[24:25], v[24:25], v[36:37]
	s_and_b64 vcc, exec, s[6:7]
	v_pk_mul_f32 v[22:23], v[22:23], v[34:35]
	global_store_dwordx4 v[26:27], v[30:33], off
	s_cbranch_vccnz .LBB0_631
	v_and_b32_e32 v29, 64, v238
	v_xor_b32_e32 v28, 16, v238
	v_add_u32_e32 v29, 64, v29
	v_cmp_lt_i32_e32 vcc, v28, v29
	s_nop 1
	v_cndmask_b32_e32 v28, v238, v28, vcc
	v_lshlrev_b32_e32 v30, 2, v28
	ds_bpermute_b32 v28, v30, v22
	ds_bpermute_b32 v29, v30, v23
	ds_bpermute_b32 v31, v30, v24
	ds_bpermute_b32 v30, v30, v25
	s_and_saveexec_b64 s[24:25], s[2:3]
	s_cbranch_execz .LBB0_630
	v_mov_b32_e32 v33, v84
	s_waitcnt lgkmcnt(2)
	v_pk_mul_f32 v[28:29], v[170:171], v[28:29]
	v_mov_b32_e32 v84, v83
	v_mov_b32_e32 v32, v82
	v_pk_mul_f32 v[28:29], v[84:85], v[28:29]
	v_mul_f32_e32 v24, v24, v78
	v_pk_fma_f32 v[22:23], v[22:23], v[32:33], v[28:29]
	s_waitcnt lgkmcnt(0)
	v_mul_f32_e32 v29, v170, v30
	v_mul_f32_e32 v28, v170, v31
	v_mov_b32_e32 v30, v25
	v_mov_b32_e32 v31, v81
	v_mov_b32_e32 v81, v29
	v_pk_mul_f32 v[30:31], v[30:31], v[80:81]
	v_mul_f32_e32 v28, v79, v28
	v_mov_b32_e32 v25, v30
	v_mov_b32_e32 v29, v31
	v_pk_add_f32 v[24:25], v[24:25], v[28:29]

.LBB0_635:
	s_waitcnt lgkmcnt(3)
	v_mul_f32_e32 v18, v209, v208
	v_cvt_pk_bf16_f32 v22, v22, v23
	v_cvt_pk_bf16_f32 v23, v24, v25
	v_cvt_pk_bf16_f32 v24, v20, v21
	v_cvt_pk_bf16_f32 v25, v28, v29
	s_waitcnt lgkmcnt(2)
	v_pk_mul_f32 v[16:17], v[16:17], v[18:19] op_sel_hi:[1,0]
	s_and_b64 vcc, exec, s[6:7]
	v_pk_mul_f32 v[14:15], v[14:15], v[18:19] op_sel_hi:[1,0]
	v_lshl_add_u64 v[26:27], v[26:27], 0, s[100:101]
	global_store_dwordx4 v[26:27], v[22:25], off
	s_cbranch_vccnz .LBB0_639
	v_and_b32_e32 v20, 64, v238
	v_xor_b32_e32 v19, 16, v238
	v_add_u32_e32 v20, 64, v20
	v_cmp_lt_i32_e32 vcc, v19, v20
	s_nop 1
	v_cndmask_b32_e32 v19, v238, v19, vcc
	v_lshlrev_b32_e32 v19, 2, v19
	ds_bpermute_b32 v20, v19, v14
	ds_bpermute_b32 v21, v19, v15
	ds_bpermute_b32 v22, v19, v16
	ds_bpermute_b32 v19, v19, v17
	s_and_saveexec_b64 s[24:25], s[2:3]
	s_cbranch_execz .LBB0_638
	s_waitcnt lgkmcnt(2)
	v_pk_mul_f32 v[20:21], v[170:171], v[20:21]
	v_mov_b32_e32 v26, v55
	v_mov_b32_e32 v27, v57
	v_mov_b32_e32 v24, v54
	v_mov_b32_e32 v25, v56
	v_pk_mul_f32 v[20:21], v[26:27], v[20:21]
	s_waitcnt lgkmcnt(0)
	v_mul_f32_e32 v23, v170, v19
	v_pk_fma_f32 v[14:15], v[14:15], v[24:25], v[20:21]
	v_mul_f32_e32 v20, v170, v22
	v_mov_b32_e32 v24, v17
	v_mov_b32_e32 v25, v53
	v_mov_b32_e32 v22, v52
	v_pk_mul_f32 v[22:23], v[24:25], v[22:23]
	v_mul_f32_e32 v16, v16, v50
	v_mul_f32_e32 v20, v51, v20
	v_mov_b32_e32 v17, v22
	v_mov_b32_e32 v21, v23
	v_pk_add_f32 v[16:17], v[16:17], v[20:21]

.LBB0_643:
	s_waitcnt lgkmcnt(3)
	v_add_u32_e32 v22, 0xb0, v176
	s_waitcnt lgkmcnt(2)
	v_ashrrev_i32_e32 v23, 31, v22
	v_mov_b64_e32 v[22:23], 0x5100
	v_cvt_pk_bf16_f32 v14, v14, v15
	v_cvt_pk_bf16_f32 v15, v16, v17
	v_cvt_pk_bf16_f32 v16, v10, v11
	v_lshl_add_u64 v[10:11], s[98:99], 0, v[22:23]
	v_cvt_pk_bf16_f32 v17, v12, v13
	v_lshl_add_u64 v[10:11], v[154:155], 1, v[10:11]
	v_pk_mul_f32 v[8:9], v[8:9], v[20:21]
	s_and_b64 vcc, exec, s[6:7]
	v_pk_mul_f32 v[6:7], v[6:7], v[18:19]
	global_store_dwordx4 v[10:11], v[14:17], off
	s_cbranch_vccnz .LBB0_647
	v_and_b32_e32 v13, 64, v238
	v_xor_b32_e32 v12, 16, v238
	v_add_u32_e32 v13, 64, v13
	v_cmp_lt_i32_e32 vcc, v12, v13
	s_nop 1
	v_cndmask_b32_e32 v12, v238, v12, vcc
	v_lshlrev_b32_e32 v14, 2, v12
	ds_bpermute_b32 v12, v14, v6
	ds_bpermute_b32 v13, v14, v7
	ds_bpermute_b32 v15, v14, v8
	ds_bpermute_b32 v14, v14, v9
	s_and_saveexec_b64 s[24:25], s[2:3]
	s_cbranch_execz .LBB0_646
	v_mov_b32_e32 v17, v56
	s_waitcnt lgkmcnt(2)
	v_pk_mul_f32 v[12:13], v[170:171], v[12:13]
	v_mov_b32_e32 v56, v55
	v_mov_b32_e32 v16, v54
	v_pk_mul_f32 v[12:13], v[56:57], v[12:13]
	v_mul_f32_e32 v8, v8, v50
	v_pk_fma_f32 v[6:7], v[6:7], v[16:17], v[12:13]
	s_waitcnt lgkmcnt(0)
	v_mul_f32_e32 v13, v170, v14
	v_mul_f32_e32 v12, v170, v15
	v_mov_b32_e32 v14, v9
	v_mov_b32_e32 v15, v53
	v_mov_b32_e32 v53, v13
	v_pk_mul_f32 v[14:15], v[14:15], v[52:53]
	v_mul_f32_e32 v12, v51, v12
	v_mov_b32_e32 v9, v14
	v_mov_b32_e32 v13, v15
	v_pk_add_f32 v[8:9], v[8:9], v[12:13]

.LBB0_651:
	v_cvt_pk_bf16_f32 v6, v6, v7
	v_cvt_pk_bf16_f32 v7, v8, v9
	v_cvt_pk_bf16_f32 v8, v2, v3
	v_cvt_pk_bf16_f32 v9, v4, v5
	s_and_b64 vcc, exec, s[4:5]
	s_mov_b64 s[4:5], -1
	v_lshl_add_u64 v[10:11], v[10:11], 0, s[100:101]
	global_store_dwordx4 v[10:11], v[6:9], off
	s_cbranch_vccnz .LBB0_502
	s_andn2_b64 vcc, exec, s[14:15]
	s_cbranch_vccnz .LBB0_501
	s_barrier
	s_branch .LBB0_501

.LBB0_677:
	s_lshr_b32 s98, s39, 4
	s_lshl_b32 s98, s98, 4
	s_lshl_b32 s99, s40, 2
	s_add_i32 s98, s98, s99
	s_lshr_b32 s99, s71, 2
	s_add_i32 s98, s98, s99
	s_lshl_b32 s98, s98, 19
	s_and_b32 s99, s39, 15
	s_lshl_b32 s99, s99, 15
	s_add_i32 s98, s98, s99
	s_add_u32 s98, s0, s98
	s_addc_u32 s99, s1, 0
	s_mov_b32 s100, 0x4000
	s_mov_b32 s101, 0
	s_lshl_b32 s4, s39, 8
	v_or_b32_e32 v122, s4, v154
	v_ashrrev_i32_e32 v123, 31, v122
	v_lshl_add_u64 v[148:149], v[122:123], 2, s[8:9]
	global_load_dwordx4 v[122:125], v[148:149], off offset:16
	global_load_dwordx4 v[134:137], v[148:149], off
	s_lshl_b32 s5, s39, 6
	v_bitop3_b32 v155, s4, v241, v154 bitop3:0xc8
	s_lshl_b32 s4, s40, 8
	s_and_b32 s5, s5, 0xfffffc00
	s_add_i32 s5, s5, s4
	v_add_u32_e32 v150, s5, v152
	v_ashrrev_i32_e32 v151, 31, v150
	v_mov_b64_e32 v[156:157], 0
	v_lshl_add_u64 v[156:157], s[98:99], 0, v[156:157]
	s_mov_b64 s[4:5], -1
	s_and_b64 vcc, exec, s[2:3]
	s_waitcnt vmcnt(0)
	v_pk_mul_f32 v[158:159], v[128:129], v[124:125]
	v_pk_mul_f32 v[132:133], v[132:133], v[136:137]
	v_pk_mul_f32 v[130:131], v[130:131], v[134:135]
	v_pk_mul_f32 v[160:161], v[126:127], v[122:123]
	v_and_b32_e32 v126, 0xffffffe0, v154
	v_lshlrev_b32_e32 v126, 7, v126
	v_and_b32_e32 v127, 31, v154
	v_lshl_add_u32 v126, v127, 6, v126
	v_and_b32_e32 v127, 15, v152
	v_lshl_add_u32 v126, v127, 4, v126
	v_mov_b32_e32 v127, v0
	v_lshl_add_u64 v[128:129], v[156:157], 0, v[126:127]
	v_cvt_pk_bf16_f32 v130, v130, v131
	v_cvt_pk_bf16_f32 v131, v132, v133
	v_cvt_pk_bf16_f32 v132, v160, v161
	v_cvt_pk_bf16_f32 v133, v158, v159
	global_store_dwordx4 v[128:129], v[130:133], off
	v_pk_mul_f32 v[120:121], v[120:121], v[136:137]
	v_pk_mul_f32 v[118:119], v[118:119], v[134:135]
	v_or_b32_e32 v130, 16, v150
	v_ashrrev_i32_e32 v131, 31, v130
	v_mov_b64_e32 v[130:131], 0x100
	v_lshl_add_u64 v[130:131], s[98:99], 0, v[130:131]
	v_pk_mul_f32 v[132:133], v[116:117], v[124:125]
	v_pk_mul_f32 v[156:157], v[114:115], v[122:123]
	v_lshl_add_u64 v[114:115], v[130:131], 0, v[126:127]
	v_cvt_pk_bf16_f32 v116, v118, v119
	v_cvt_pk_bf16_f32 v117, v120, v121
	v_cvt_pk_bf16_f32 v118, v156, v157
	v_cvt_pk_bf16_f32 v119, v132, v133
	global_store_dwordx4 v[114:115], v[116:119], off
	v_pk_mul_f32 v[112:113], v[112:113], v[136:137]
	v_pk_mul_f32 v[110:111], v[110:111], v[134:135]
	v_or_b32_e32 v116, 32, v150
	v_ashrrev_i32_e32 v117, 31, v116
	v_mov_b64_e32 v[116:117], 0x800
	v_lshl_add_u64 v[116:117], s[98:99], 0, v[116:117]
	v_pk_mul_f32 v[118:119], v[108:109], v[124:125]
	v_pk_mul_f32 v[120:121], v[106:107], v[122:123]
	v_lshl_add_u64 v[106:107], v[116:117], 0, v[126:127]
	v_cvt_pk_bf16_f32 v108, v110, v111
	v_cvt_pk_bf16_f32 v109, v112, v113
	v_cvt_pk_bf16_f32 v110, v120, v121
	v_cvt_pk_bf16_f32 v111, v118, v119
	global_store_dwordx4 v[106:107], v[108:111], off
	v_pk_mul_f32 v[104:105], v[104:105], v[136:137]
	v_pk_mul_f32 v[102:103], v[102:103], v[134:135]
	v_or_b32_e32 v108, 48, v150
	v_ashrrev_i32_e32 v109, 31, v108
	v_mov_b64_e32 v[108:109], 0x900
	v_lshl_add_u64 v[108:109], s[98:99], 0, v[108:109]
	v_pk_mul_f32 v[110:111], v[100:101], v[124:125]
	v_pk_mul_f32 v[112:113], v[98:99], v[122:123]
	v_lshl_add_u64 v[98:99], v[108:109], 0, v[126:127]
	v_cvt_pk_bf16_f32 v100, v102, v103
	v_cvt_pk_bf16_f32 v101, v104, v105
	v_cvt_pk_bf16_f32 v102, v112, v113
	v_cvt_pk_bf16_f32 v103, v110, v111
	global_store_dwordx4 v[98:99], v[100:103], off
	v_pk_mul_f32 v[96:97], v[96:97], v[136:137]
	v_pk_mul_f32 v[94:95], v[94:95], v[134:135]
	v_add_u32_e32 v100, 0x80, v150
	v_ashrrev_i32_e32 v101, 31, v100
	v_mov_b64_e32 v[100:101], 0x100000
	v_lshl_add_u64 v[100:101], s[98:99], 0, v[100:101]
	v_pk_mul_f32 v[102:103], v[92:93], v[124:125]
	v_pk_mul_f32 v[104:105], v[90:91], v[122:123]
	v_lshl_add_u64 v[90:91], v[100:101], 0, v[126:127]
	v_cvt_pk_bf16_f32 v92, v94, v95
	v_cvt_pk_bf16_f32 v93, v96, v97
	v_cvt_pk_bf16_f32 v94, v104, v105
	v_cvt_pk_bf16_f32 v95, v102, v103
	global_store_dwordx4 v[90:91], v[92:95], off
	v_pk_mul_f32 v[88:89], v[88:89], v[136:137]
	v_pk_mul_f32 v[86:87], v[86:87], v[134:135]
	v_add_u32_e32 v92, 0x90, v150
	v_ashrrev_i32_e32 v93, 31, v92
	v_mov_b64_e32 v[92:93], 0x100100
	v_lshl_add_u64 v[92:93], s[98:99], 0, v[92:93]
	v_pk_mul_f32 v[94:95], v[84:85], v[124:125]
	v_pk_mul_f32 v[96:97], v[82:83], v[122:123]
	v_lshl_add_u64 v[82:83], v[92:93], 0, v[126:127]
	v_cvt_pk_bf16_f32 v84, v86, v87
	v_cvt_pk_bf16_f32 v85, v88, v89
	v_cvt_pk_bf16_f32 v86, v96, v97
	v_cvt_pk_bf16_f32 v87, v94, v95
	global_store_dwordx4 v[82:83], v[84:87], off
	v_pk_mul_f32 v[80:81], v[80:81], v[136:137]
	v_pk_mul_f32 v[78:79], v[78:79], v[134:135]
	v_add_u32_e32 v84, 0xa0, v150
	v_ashrrev_i32_e32 v85, 31, v84
	v_pk_mul_f32 v[72:73], v[72:73], v[124:125]
	v_mov_b64_e32 v[84:85], 0x100800
	v_cvt_pk_bf16_f32 v78, v78, v79
	v_cvt_pk_bf16_f32 v79, v80, v81
	v_cvt_pk_bf16_f32 v81, v72, v73
	v_add_u32_e32 v72, 0xb0, v150
	v_lshl_add_u64 v[84:85], s[98:99], 0, v[84:85]
	v_pk_mul_f32 v[86:87], v[70:71], v[122:123]
	v_ashrrev_i32_e32 v73, 31, v72
	v_lshl_add_u64 v[70:71], v[84:85], 0, v[126:127]
	v_cvt_pk_bf16_f32 v80, v86, v87
	v_mov_b64_e32 v[72:73], 0x100900
	global_store_dwordx4 v[70:71], v[78:81], off
	v_lshl_add_u64 v[72:73], s[98:99], 0, v[72:73]
	v_pk_mul_f32 v[64:65], v[64:65], v[136:137]
	v_pk_mul_f32 v[62:63], v[62:63], v[134:135]
	v_pk_mul_f32 v[78:79], v[60:61], v[124:125]
	v_pk_mul_f32 v[60:61], v[58:59], v[122:123]
	v_lshl_add_u64 v[72:73], v[72:73], 0, v[126:127]
	v_cvt_pk_bf16_f32 v58, v62, v63
	v_cvt_pk_bf16_f32 v59, v64, v65
	v_cvt_pk_bf16_f32 v60, v60, v61
	v_cvt_pk_bf16_f32 v61, v78, v79
	global_store_dwordx4 v[72:73], v[58:61], off
	global_load_dwordx4 v[58:61], v[148:149], off offset:528
	s_nop 0
	global_load_dwordx4 v[62:65], v[148:149], off offset:512
	s_waitcnt vmcnt(1)
	v_pk_mul_f32 v[78:79], v[68:69], v[60:61]
	s_waitcnt vmcnt(0)
	v_pk_mul_f32 v[76:77], v[76:77], v[64:65]
	v_pk_mul_f32 v[74:75], v[74:75], v[62:63]
	v_pk_mul_f32 v[68:69], v[66:67], v[58:59]
	v_cvt_pk_bf16_f32 v66, v74, v75
	v_cvt_pk_bf16_f32 v67, v76, v77
	v_cvt_pk_bf16_f32 v68, v68, v69
	v_cvt_pk_bf16_f32 v69, v78, v79
	v_lshl_add_u64 v[128:129], v[128:129], 0, s[100:101]
	global_store_dwordx4 v[128:129], v[66:69], off
	v_pk_mul_f32 v[56:57], v[56:57], v[64:65]
	v_pk_mul_f32 v[54:55], v[54:55], v[62:63]
	v_pk_mul_f32 v[66:67], v[52:53], v[60:61]
	v_pk_mul_f32 v[52:53], v[50:51], v[58:59]
	v_cvt_pk_bf16_f32 v50, v54, v55
	v_cvt_pk_bf16_f32 v51, v56, v57
	v_cvt_pk_bf16_f32 v52, v52, v53
	v_cvt_pk_bf16_f32 v53, v66, v67
	v_lshl_add_u64 v[114:115], v[114:115], 0, s[100:101]
	global_store_dwordx4 v[114:115], v[50:53], off
	v_pk_mul_f32 v[48:49], v[48:49], v[64:65]
	v_pk_mul_f32 v[46:47], v[46:47], v[62:63]
	v_pk_mul_f32 v[50:51], v[44:45], v[60:61]
	v_pk_mul_f32 v[44:45], v[42:43], v[58:59]
	v_cvt_pk_bf16_f32 v42, v46, v47
	v_cvt_pk_bf16_f32 v43, v48, v49
	v_cvt_pk_bf16_f32 v44, v44, v45
	v_cvt_pk_bf16_f32 v45, v50, v51
	v_lshl_add_u64 v[106:107], v[106:107], 0, s[100:101]
	global_store_dwordx4 v[106:107], v[42:45], off
	v_pk_mul_f32 v[40:41], v[40:41], v[64:65]
	v_pk_mul_f32 v[38:39], v[38:39], v[62:63]
	v_pk_mul_f32 v[42:43], v[36:37], v[60:61]
	v_pk_mul_f32 v[36:37], v[34:35], v[58:59]
	v_cvt_pk_bf16_f32 v34, v38, v39
	v_cvt_pk_bf16_f32 v35, v40, v41
	v_cvt_pk_bf16_f32 v36, v36, v37
	v_cvt_pk_bf16_f32 v37, v42, v43
	v_lshl_add_u64 v[98:99], v[98:99], 0, s[100:101]
	global_store_dwordx4 v[98:99], v[34:37], off
	v_pk_mul_f32 v[32:33], v[32:33], v[64:65]
	v_pk_mul_f32 v[30:31], v[30:31], v[62:63]
	v_pk_mul_f32 v[34:35], v[28:29], v[60:61]
	v_pk_mul_f32 v[28:29], v[26:27], v[58:59]
	v_cvt_pk_bf16_f32 v26, v30, v31
	v_cvt_pk_bf16_f32 v27, v32, v33
	v_cvt_pk_bf16_f32 v28, v28, v29
	v_cvt_pk_bf16_f32 v29, v34, v35
	v_lshl_add_u64 v[90:91], v[90:91], 0, s[100:101]
	global_store_dwordx4 v[90:91], v[26:29], off
	v_pk_mul_f32 v[24:25], v[24:25], v[64:65]
	v_pk_mul_f32 v[22:23], v[22:23], v[62:63]
	v_pk_mul_f32 v[26:27], v[20:21], v[60:61]
	v_pk_mul_f32 v[20:21], v[18:19], v[58:59]
	v_cvt_pk_bf16_f32 v18, v22, v23
	v_cvt_pk_bf16_f32 v19, v24, v25
	v_cvt_pk_bf16_f32 v20, v20, v21
	v_cvt_pk_bf16_f32 v21, v26, v27
	v_lshl_add_u64 v[82:83], v[82:83], 0, s[100:101]
	global_store_dwordx4 v[82:83], v[18:21], off
	v_pk_mul_f32 v[16:17], v[16:17], v[64:65]
	v_pk_mul_f32 v[14:15], v[14:15], v[62:63]
	v_pk_mul_f32 v[18:19], v[12:13], v[60:61]
	v_pk_mul_f32 v[12:13], v[10:11], v[58:59]
	v_cvt_pk_bf16_f32 v10, v14, v15
	v_cvt_pk_bf16_f32 v11, v16, v17
	v_cvt_pk_bf16_f32 v12, v12, v13
	v_cvt_pk_bf16_f32 v13, v18, v19
	v_lshl_add_u64 v[70:71], v[70:71], 0, s[100:101]
	global_store_dwordx4 v[70:71], v[10:13], off
	v_pk_mul_f32 v[8:9], v[8:9], v[64:65]
	v_pk_mul_f32 v[6:7], v[6:7], v[62:63]
	v_pk_mul_f32 v[10:11], v[4:5], v[60:61]
	v_pk_mul_f32 v[4:5], v[2:3], v[58:59]
	v_cvt_pk_bf16_f32 v2, v6, v7
	v_cvt_pk_bf16_f32 v3, v8, v9
	v_cvt_pk_bf16_f32 v4, v4, v5
	v_cvt_pk_bf16_f32 v5, v10, v11
	v_lshl_add_u64 v[72:73], v[72:73], 0, s[100:101]
	global_store_dwordx4 v[72:73], v[2:5], off
	s_cbranch_vccnz .LBB0_664
	s_andn2_b64 vcc, exec, s[6:7]
	s_cbranch_vccnz .LBB0_663
	s_barrier
	s_branch .LBB0_663
